# gemm1 k-step rewritten: own register quad for the second A fragment, one counted wait per k16 group, reads behind the freeing MFMAs, stores two per group
# speedup vs baseline: 1.0046x; 1.0046x over previous
.LBB0_176:
	s_add_i32 s20, s71, 2
	s_cmp_lt_i32 s20, s90
	s_cselect_b64 s[82:83], -1, 0
	s_cmp_ge_i32 s20, s90
	s_cselect_b64 s[80:81], -1, 0
	s_and_b64 vcc, exec, s[80:81]
	v_add_u32_e32 v157, v137, v139
	v_add_u32_e32 v165, v137, v141
	ds_read_b128 v[198:201], v157
	ds_read_b128 v[202:205], v165 offset:16384
	ds_read_b128 v[206:209], v165 offset:20480
	ds_read_b128 v[242:245], v157 offset:4096
	s_cbranch_vccnz .LBB0_180
	s_add_i32 s74, s15, 0x800
	s_cmp_lt_u32 s71, 14
	s_cselect_b64 s[84:85], -1, 0
	s_and_b64 vcc, s[84:85], exec
	s_cselect_b32 vcc_lo, s74, s15
	v_mov_b32_e32 v81, v80
	s_ashr_i32 vcc_hi, vcc_lo, 31
	v_mov_b32_e32 v82, v80
	v_mov_b32_e32 v83, v80
	s_waitcnt vmcnt(8)
	v_mov_b64_e32 v[64:65], v[80:81]
	v_lshl_add_u64 v[120:121], vcc, 1, v[178:179]
	s_or_b64 vcc, s[84:85], s[4:5]
	v_mov_b64_e32 v[66:67], v[82:83]
	s_and_saveexec_b64 s[84:85], vcc
	s_cbranch_execz .LBB0_179
	global_load_dwordx4 v[64:67], v[120:121], off

.Lm1w_w1:
	v_add_u32_e32 v159, v143, v139
	v_add_u32_e32 v167, v143, v141
	v_add_u32_e32 v161, v153, v139
	v_add_u32_e32 v169, v153, v141
	v_add_u32_e32 v163, v155, v139
	v_add_u32_e32 v171, v155, v141
	ds_write_b128 v135, v[68:71] offset:32768
	ds_write_b128 v135, v[72:75] offset:49152
	s_waitcnt lgkmcnt(2)
	v_mfma_f32_32x32x16_bf16 v[48:63], v[198:201], v[202:205], v[48:63]
	s_add_i32 s21, s71, 3
	s_cmp_ge_i32 s21, s90
	v_mfma_f32_32x32x16_bf16 v[32:47], v[198:201], v[206:209], v[32:47]
	ds_read_b128 v[198:201], v159
	v_mfma_f32_32x32x16_bf16 v[16:31], v[242:245], v[202:205], v[16:31]
	ds_read_b128 v[202:205], v167 offset:16384
	v_mfma_f32_32x32x16_bf16 v[0:15], v[242:245], v[206:209], v[0:15]
	ds_read_b128 v[206:209], v167 offset:20480
	ds_read_b128 v[242:245], v159 offset:4096
	ds_write_b128 v135, v[92:95] offset:36864
	ds_write_b128 v135, v[84:87] offset:53248
	s_waitcnt lgkmcnt(2)
	v_mfma_f32_32x32x16_bf16 v[48:63], v[198:201], v[202:205], v[48:63]
	v_mfma_f32_32x32x16_bf16 v[32:47], v[198:201], v[206:209], v[32:47]
	ds_read_b128 v[198:201], v161
	v_mfma_f32_32x32x16_bf16 v[16:31], v[242:245], v[202:205], v[16:31]
	ds_read_b128 v[202:205], v169 offset:16384
	v_mfma_f32_32x32x16_bf16 v[0:15], v[242:245], v[206:209], v[0:15]
	ds_read_b128 v[206:209], v169 offset:20480
	ds_read_b128 v[242:245], v161 offset:4096
	ds_write_b128 v135, v[108:111] offset:40960
	ds_write_b128 v135, v[100:103] offset:57344
	s_waitcnt lgkmcnt(2)
	v_mfma_f32_32x32x16_bf16 v[48:63], v[198:201], v[202:205], v[48:63]
	v_mfma_f32_32x32x16_bf16 v[32:47], v[198:201], v[206:209], v[32:47]
	ds_read_b128 v[198:201], v163
	v_mfma_f32_32x32x16_bf16 v[16:31], v[242:245], v[202:205], v[16:31]
	ds_read_b128 v[202:205], v171 offset:16384
	v_mfma_f32_32x32x16_bf16 v[0:15], v[242:245], v[206:209], v[0:15]
	ds_read_b128 v[206:209], v171 offset:20480
	ds_read_b128 v[242:245], v163 offset:4096
	ds_write_b128 v135, v[124:127] offset:45056
	ds_write_b128 v135, v[116:119] offset:61440
	s_waitcnt lgkmcnt(2)
	v_mfma_f32_32x32x16_bf16 v[48:63], v[198:201], v[202:205], v[48:63]
	v_mfma_f32_32x32x16_bf16 v[32:47], v[198:201], v[206:209], v[32:47]
	v_mfma_f32_32x32x16_bf16 v[16:31], v[242:245], v[202:205], v[16:31]
	v_mfma_f32_32x32x16_bf16 v[0:15], v[242:245], v[206:209], v[0:15]
	s_waitcnt lgkmcnt(0)
	s_barrier
	ds_read_b128 v[198:201], v157 offset:32768
	ds_read_b128 v[202:205], v165 offset:49152
	ds_read_b128 v[206:209], v165 offset:53248
	ds_read_b128 v[242:245], v157 offset:36864
	s_cbranch_scc1 .LBB0_184
	s_add_i32 s21, s15, 64
	s_add_i32 s74, s15, 0x840
	s_cmp_lt_u32 s71, 13
	s_cselect_b64 s[84:85], -1, 0
	s_and_b64 vcc, s[84:85], exec
	s_cselect_b32 vcc_lo, s74, s21
	v_mov_b32_e32 v81, v80
	s_ashr_i32 vcc_hi, vcc_lo, 31
	v_mov_b32_e32 v82, v80
	v_mov_b32_e32 v83, v80
	v_mov_b64_e32 v[68:69], v[80:81]
	v_lshl_add_u64 v[116:117], vcc, 1, v[178:179]
	s_or_b64 vcc, s[84:85], s[4:5]
	v_mov_b64_e32 v[70:71], v[82:83]
	s_and_saveexec_b64 s[84:85], vcc
	s_cbranch_execz .LBB0_183
	global_load_dwordx4 v[68:71], v[116:117], off

.LBB0_184:
	s_waitcnt vmcnt(8)
	ds_write_b128 v135, v[64:67]
	ds_write_b128 v135, v[76:79] offset:16384
	s_waitcnt lgkmcnt(2)
	v_mfma_f32_32x32x16_bf16 v[48:63], v[198:201], v[202:205], v[48:63]
	v_mfma_f32_32x32x16_bf16 v[32:47], v[198:201], v[206:209], v[32:47]
	ds_read_b128 v[198:201], v159 offset:32768
	v_mfma_f32_32x32x16_bf16 v[16:31], v[242:245], v[202:205], v[16:31]
	ds_read_b128 v[202:205], v167 offset:49152
	v_mfma_f32_32x32x16_bf16 v[0:15], v[242:245], v[206:209], v[0:15]
	ds_read_b128 v[206:209], v167 offset:53248
	ds_read_b128 v[242:245], v159 offset:36864
	ds_write_b128 v135, v[96:99] offset:4096
	ds_write_b128 v135, v[88:91] offset:20480
	s_waitcnt lgkmcnt(2)
	v_mfma_f32_32x32x16_bf16 v[48:63], v[198:201], v[202:205], v[48:63]
	v_mfma_f32_32x32x16_bf16 v[32:47], v[198:201], v[206:209], v[32:47]
	ds_read_b128 v[198:201], v161 offset:32768
	v_mfma_f32_32x32x16_bf16 v[16:31], v[242:245], v[202:205], v[16:31]
	ds_read_b128 v[202:205], v169 offset:49152
	v_mfma_f32_32x32x16_bf16 v[0:15], v[242:245], v[206:209], v[0:15]
	ds_read_b128 v[206:209], v169 offset:53248
	ds_read_b128 v[242:245], v161 offset:36864
	ds_write_b128 v135, v[112:115] offset:8192
	ds_write_b128 v135, v[104:107] offset:24576
	s_waitcnt lgkmcnt(2)
	v_mfma_f32_32x32x16_bf16 v[48:63], v[198:201], v[202:205], v[48:63]
	v_mfma_f32_32x32x16_bf16 v[32:47], v[198:201], v[206:209], v[32:47]
	ds_read_b128 v[198:201], v163 offset:32768
	v_mfma_f32_32x32x16_bf16 v[16:31], v[242:245], v[202:205], v[16:31]
	ds_read_b128 v[202:205], v171 offset:49152
	v_mfma_f32_32x32x16_bf16 v[0:15], v[242:245], v[206:209], v[0:15]
	ds_read_b128 v[206:209], v171 offset:53248
	ds_read_b128 v[242:245], v163 offset:36864
	ds_write_b128 v135, v[128:131] offset:12288
	ds_write_b128 v135, v[120:123] offset:28672
	s_waitcnt lgkmcnt(2)
	v_mfma_f32_32x32x16_bf16 v[48:63], v[198:201], v[202:205], v[48:63]
	v_mfma_f32_32x32x16_bf16 v[32:47], v[198:201], v[206:209], v[32:47]
	v_mfma_f32_32x32x16_bf16 v[16:31], v[242:245], v[202:205], v[16:31]
	v_mfma_f32_32x32x16_bf16 v[0:15], v[242:245], v[206:209], v[0:15]
